# v107 + removed six dead lane-index VALU instructions per attention head iteration (left over from ds_bpermute replacement)
# baseline (speedup 1.0000x reference)
.LBB0_2056:
	v_mov_b32_e32 v96, v101
	ds_read_b128 v[0:3], v135
	ds_read_b128 v[4:7], v135 offset:32
	s_load_dwordx2 s[0:1], s[40:41], 0x80
	s_add_i32 s39, s45, s38
	s_waitcnt lgkmcnt(0)
	v_mfma_f32_32x32x16_bf16 v[64:79], v[0:3], v[80:83], 0
	ds_read_b128 v[0:3], v135 offset:64
	s_add_u32 s0, s0, s36
	s_addc_u32 s1, s1, s37
	s_add_i32 s38, s38, 1
	s_nop 0
	v_mfma_f32_32x32x16_bf16 v[64:79], v[4:7], v[84:87], v[64:79]
	s_waitcnt lgkmcnt(0)
	v_mfma_f32_32x32x16_bf16 v[64:79], v[0:3], v[88:91], v[64:79]
	ds_read_b128 v[0:3], v135 offset:96
	s_waitcnt lgkmcnt(0)
	v_mfma_f32_32x32x16_bf16 v[64:79], v[0:3], v[92:95], v[64:79]
	ds_read_b128 v[0:3], v135 offset:4608
	s_waitcnt lgkmcnt(0)
	v_mfma_f32_32x32x16_bf16 v[48:63], v[0:3], v[80:83], 0
	ds_read_b128 v[0:3], v135 offset:4640
	s_waitcnt lgkmcnt(0)
	v_mfma_f32_32x32x16_bf16 v[48:63], v[0:3], v[84:87], v[48:63]
	ds_read_b128 v[0:3], v135 offset:4672
	s_waitcnt lgkmcnt(0)
	v_mfma_f32_32x32x16_bf16 v[48:63], v[0:3], v[88:91], v[48:63]
	ds_read_b128 v[0:3], v135 offset:4704
	s_waitcnt lgkmcnt(0)
	v_mfma_f32_32x32x16_bf16 v[48:63], v[0:3], v[92:95], v[48:63]
	ds_read_b128 v[0:3], v135 offset:9216
	s_waitcnt lgkmcnt(0)
	v_mfma_f32_32x32x16_bf16 v[32:47], v[0:3], v[80:83], 0
	ds_read_b128 v[0:3], v135 offset:9248
	s_waitcnt lgkmcnt(0)
	v_mfma_f32_32x32x16_bf16 v[32:47], v[0:3], v[84:87], v[32:47]
	ds_read_b128 v[0:3], v135 offset:9280
	s_waitcnt lgkmcnt(0)
	v_mfma_f32_32x32x16_bf16 v[32:47], v[0:3], v[88:91], v[32:47]
	ds_read_b128 v[0:3], v135 offset:9312
	s_waitcnt lgkmcnt(0)
	v_mfma_f32_32x32x16_bf16 v[32:47], v[0:3], v[92:95], v[32:47]
	ds_read_b128 v[0:3], v135 offset:13824
	s_waitcnt lgkmcnt(0)
	v_mfma_f32_32x32x16_bf16 v[16:31], v[0:3], v[80:83], 0
	ds_read_b128 v[0:3], v135 offset:13856
	s_waitcnt lgkmcnt(0)
	v_mfma_f32_32x32x16_bf16 v[16:31], v[0:3], v[84:87], v[16:31]
	ds_read_b128 v[0:3], v135 offset:13888
	s_waitcnt lgkmcnt(0)
	v_mfma_f32_32x32x16_bf16 v[16:31], v[0:3], v[88:91], v[16:31]
	ds_read_b128 v[0:3], v135 offset:13920
	s_waitcnt lgkmcnt(0)
	v_mfma_f32_32x32x16_bf16 v[16:31], v[0:3], v[92:95], v[16:31]
	ds_read_b128 v[0:3], v135 offset:18432
	s_waitcnt lgkmcnt(0)
	v_mfma_f32_32x32x16_bf16 v[0:15], v[0:3], v[80:83], 0
	ds_read_b128 v[80:83], v135 offset:18464
	s_waitcnt lgkmcnt(0)
	v_mfma_f32_32x32x16_bf16 v[0:15], v[80:83], v[84:87], v[0:15]
	ds_read_b128 v[80:83], v135 offset:18496
	s_waitcnt lgkmcnt(0)
	v_mfma_f32_32x32x16_bf16 v[0:15], v[80:83], v[88:91], v[0:15]
	ds_read_b128 v[80:83], v135 offset:18528
	s_waitcnt lgkmcnt(0)
	v_mfma_f32_32x32x16_bf16 v[0:15], v[80:83], v[92:95], v[0:15]
	global_load_dword v80, v97, s[0:1]
	v_add_u32_e32 v94, 0x80, v96
	v_cmp_le_i32_e64 s[0:1], v100, v96
	v_cmp_gt_i32_e32 vcc, v100, v94
	s_or_b64 s[0:1], s[0:1], vcc
	v_readlane_b32 vcc_lo, v254, 37
	v_readlane_b32 vcc_hi, v254, 38
	s_or_b64 vcc, s[0:1], vcc
	v_cmp_ge_i32_e64 s[0:1], v100, v94
	v_cndmask_b32_e32 v64, v64, v200, vcc
	v_cmp_lt_i32_e32 vcc, v100, v96
	s_or_b64 s[0:1], vcc, s[0:1]
	v_readlane_b32 vcc_lo, v254, 39
	v_readlane_b32 vcc_hi, v254, 40
	s_or_b64 vcc, s[0:1], vcc
	v_cmp_gt_i32_e64 s[0:1], v104, v94
	v_cndmask_b32_e32 v65, v65, v200, vcc
	v_cmp_le_i32_e32 vcc, v104, v96
	s_or_b64 s[0:1], vcc, s[0:1]
	v_readlane_b32 vcc_lo, v254, 20
	v_readlane_b32 vcc_hi, v254, 21
	s_or_b64 vcc, s[0:1], vcc
	v_cmp_gt_i32_e64 s[0:1], v105, v94
	v_cndmask_b32_e32 v66, v66, v200, vcc
	v_cmp_le_i32_e32 vcc, v105, v96
	s_or_b64 s[0:1], vcc, s[0:1]
	v_readlane_b32 vcc_lo, v254, 18
	v_readlane_b32 vcc_hi, v254, 19
	s_or_b64 vcc, s[0:1], vcc
	v_cmp_gt_i32_e64 s[0:1], v106, v94
	v_cndmask_b32_e32 v67, v67, v200, vcc
	v_cmp_le_i32_e32 vcc, v106, v96
	s_or_b64 s[0:1], vcc, s[0:1]
	v_readlane_b32 vcc_lo, v254, 41
	v_readlane_b32 vcc_hi, v254, 42
	s_or_b64 vcc, s[0:1], vcc
	v_cmp_gt_i32_e64 s[0:1], v107, v94
	v_cndmask_b32_e32 v68, v68, v200, vcc
	v_cmp_le_i32_e32 vcc, v107, v96
	s_or_b64 s[0:1], vcc, s[0:1]
	v_readlane_b32 vcc_lo, v254, 22
	v_readlane_b32 vcc_hi, v254, 23
	s_or_b64 vcc, s[0:1], vcc
	v_cmp_gt_i32_e64 s[0:1], v108, v94
	v_cndmask_b32_e32 v69, v69, v200, vcc
	v_cmp_le_i32_e32 vcc, v108, v96
	s_or_b64 s[0:1], vcc, s[0:1]
	v_readlane_b32 vcc_lo, v254, 24
	v_readlane_b32 vcc_hi, v254, 25
	s_or_b64 vcc, s[0:1], vcc
	v_cmp_gt_i32_e64 s[0:1], v109, v94
	v_cndmask_b32_e32 v70, v70, v200, vcc
	v_cmp_le_i32_e32 vcc, v109, v96
	s_or_b64 s[0:1], vcc, s[0:1]
	v_readlane_b32 vcc_lo, v254, 26
	v_readlane_b32 vcc_hi, v254, 27
	s_or_b64 vcc, s[0:1], vcc
	v_cmp_gt_i32_e64 s[0:1], v110, v94
	v_cndmask_b32_e32 v71, v71, v200, vcc
	v_cmp_le_i32_e32 vcc, v110, v96
	s_or_b64 s[0:1], vcc, s[0:1]
	v_readlane_b32 vcc_lo, v254, 28
	v_readlane_b32 vcc_hi, v254, 29
	s_or_b64 vcc, s[0:1], vcc
	v_cmp_gt_i32_e64 s[0:1], v111, v94
	v_cndmask_b32_e32 v72, v72, v200, vcc
	v_cmp_le_i32_e32 vcc, v111, v96
	s_or_b64 s[0:1], vcc, s[0:1]
	v_readlane_b32 vcc_lo, v254, 32
	v_readlane_b32 vcc_hi, v254, 33
	s_or_b64 vcc, s[0:1], vcc
	v_cmp_gt_i32_e64 s[0:1], v112, v94
	v_cndmask_b32_e32 v73, v73, v200, vcc
	v_cmp_le_i32_e32 vcc, v112, v96
	s_or_b64 s[0:1], vcc, s[0:1]
	v_readlane_b32 vcc_lo, v254, 34
	v_readlane_b32 vcc_hi, v254, 35
	s_or_b64 vcc, s[0:1], vcc
	v_cmp_gt_i32_e64 s[0:1], v113, v94
	v_cndmask_b32_e32 v74, v74, v200, vcc
	v_cmp_le_i32_e32 vcc, v113, v96
	s_or_b64 s[0:1], vcc, s[0:1]
	v_readlane_b32 vcc_lo, v254, 5
	v_readlane_b32 vcc_hi, v254, 6
	s_or_b64 vcc, s[0:1], vcc
	v_cmp_gt_i32_e64 s[0:1], v114, v94
	v_cndmask_b32_e32 v75, v75, v200, vcc
	v_cmp_le_i32_e32 vcc, v114, v96
	s_or_b64 s[0:1], vcc, s[0:1]
	v_readlane_b32 vcc_lo, v254, 8
	v_readlane_b32 vcc_hi, v254, 9
	s_or_b64 vcc, s[0:1], vcc
	v_cmp_gt_i32_e64 s[0:1], v115, v94
	v_cndmask_b32_e32 v76, v76, v200, vcc
	v_cmp_le_i32_e32 vcc, v115, v96
	s_or_b64 s[0:1], vcc, s[0:1]
	v_readlane_b32 vcc_lo, v254, 30
	v_readlane_b32 vcc_hi, v254, 31
	s_or_b64 vcc, s[0:1], vcc
	v_cmp_gt_i32_e64 s[0:1], v116, v94
	v_cndmask_b32_e32 v77, v77, v200, vcc
	v_cmp_le_i32_e32 vcc, v116, v96
	s_or_b64 s[0:1], vcc, s[0:1]
	v_readlane_b32 vcc_lo, v254, 58
	v_readlane_b32 vcc_hi, v254, 59
	s_or_b64 vcc, s[0:1], vcc
	v_cmp_gt_i32_e64 s[0:1], v117, v94
	v_cndmask_b32_e32 v85, v78, v200, vcc
	v_cmp_le_i32_e32 vcc, v117, v96
	s_or_b64 s[0:1], vcc, s[0:1]
	v_readlane_b32 vcc_lo, v254, 60
	v_readlane_b32 vcc_hi, v254, 61
	s_or_b64 vcc, s[0:1], vcc
	v_readlane_b32 s0, v254, 62
	v_readlane_b32 s1, v254, 63
	s_waitcnt vmcnt(0)
	v_max3_f32 v81, v80, v64, v65
	v_max3_f32 v81, v81, v66, v67
	v_cndmask_b32_e64 v93, v48, v200, s[0:1]
	v_readlane_b32 s0, v255, 0
	v_readlane_b32 s1, v255, 1
	v_max3_f32 v81, v81, v68, v69
	v_max3_f32 v81, v81, v70, v71
	v_cndmask_b32_e64 v90, v49, v200, s[0:1]
	v_readlane_b32 s0, v255, 2
	v_readlane_b32 s1, v255, 3
	v_max3_f32 v81, v81, v72, v73
	v_max3_f32 v81, v81, v74, v75
	v_cndmask_b32_e64 v91, v50, v200, s[0:1]
	v_readlane_b32 s0, v255, 4
	v_readlane_b32 s1, v255, 5
	v_max3_f32 v81, v81, v76, v77
	v_cndmask_b32_e32 v92, v79, v200, vcc
	v_cndmask_b32_e64 v88, v51, v200, s[0:1]
	v_readlane_b32 s0, v255, 6
	v_readlane_b32 s1, v255, 7
	v_max3_f32 v78, v81, v85, v92
	v_max3_f32 v48, v78, v93, v90
	v_cndmask_b32_e64 v89, v52, v200, s[0:1]
	v_readlane_b32 s0, v255, 8
	v_readlane_b32 s1, v255, 9
	v_cmp_le_i32_e32 vcc, v118, v96
	v_max3_f32 v48, v48, v91, v88
	v_cndmask_b32_e64 v86, v53, v200, s[0:1]
	v_readlane_b32 s0, v255, 10
	v_readlane_b32 s1, v255, 11
	v_max3_f32 v48, v48, v89, v86
	v_cndmask_b32_e64 v52, v39, v200, s[6:7]
	v_cndmask_b32_e64 v87, v54, v200, s[0:1]
	v_readlane_b32 s0, v255, 12
	v_readlane_b32 s1, v255, 13
	v_cndmask_b32_e64 v51, v40, v200, s[50:51]
	v_cndmask_b32_e64 v50, v41, v200, s[52:53]
	v_cndmask_b32_e64 v83, v55, v200, s[0:1]
	v_readlane_b32 s0, v255, 14
	v_readlane_b32 s1, v255, 15
	v_max3_f32 v48, v48, v87, v83
	v_cndmask_b32_e64 v49, v42, v200, s[54:55]
	v_cndmask_b32_e64 v84, v56, v200, s[0:1]
	v_readlane_b32 s0, v255, 16
	v_readlane_b32 s1, v255, 17
	v_cndmask_b32_e64 v42, v45, v200, s[60:61]
	v_cndmask_b32_e64 v41, v46, v200, s[62:63]
	v_cndmask_b32_e64 v81, v57, v200, s[0:1]
	v_readlane_b32 s0, v255, 18
	v_readlane_b32 s1, v255, 19
	v_max3_f32 v48, v48, v84, v81
	v_cndmask_b32_e64 v40, v47, v200, s[64:65]
	v_cndmask_b32_e64 v82, v58, v200, s[0:1]
	v_readlane_b32 s0, v255, 20
	v_readlane_b32 s1, v255, 21
	v_cndmask_b32_e64 v39, v16, v200, s[66:67]
	s_nop 0
	v_cndmask_b32_e64 v78, v59, v200, s[0:1]
	v_readlane_b32 s0, v255, 22
	v_readlane_b32 s1, v255, 23
	v_max3_f32 v48, v48, v82, v78
	s_nop 0
	v_cndmask_b32_e64 v79, v60, v200, s[0:1]
	v_readlane_b32 s0, v255, 24
	v_readlane_b32 s1, v255, 25
	s_nop 1
	v_cndmask_b32_e64 v61, v61, v200, s[0:1]
	v_readlane_b32 s0, v255, 26
	v_readlane_b32 s1, v255, 27
	v_max3_f32 v48, v48, v79, v61
	s_nop 0
	v_cndmask_b32_e64 v62, v62, v200, s[0:1]
	v_readlane_b32 s0, v255, 28
	v_readlane_b32 s1, v255, 29
	s_nop 1
	v_cndmask_b32_e64 v59, v63, v200, s[0:1]
	v_readlane_b32 s0, v255, 30
	v_readlane_b32 s1, v255, 31
	v_max3_f32 v48, v48, v62, v59
	s_nop 0
	v_cndmask_b32_e64 v60, v32, v200, s[0:1]
	v_readlane_b32 s0, v255, 32
	v_readlane_b32 s1, v255, 33
	s_nop 1
	v_cndmask_b32_e64 v57, v33, v200, s[0:1]
	v_readlane_b32 s0, v255, 34
	v_readlane_b32 s1, v255, 35
	v_max3_f32 v32, v48, v60, v57
	v_cndmask_b32_e64 v48, v43, v200, s[56:57]
	v_cndmask_b32_e64 v58, v34, v200, s[0:1]
	v_readlane_b32 s0, v255, 36
	v_readlane_b32 s1, v255, 37
	v_cndmask_b32_e64 v43, v44, v200, s[58:59]
	v_cndmask_b32_e64 v34, v21, v200, s[76:77]
	v_cndmask_b32_e64 v55, v35, v200, s[0:1]
	v_readlane_b32 s0, v255, 38
	v_readlane_b32 s1, v255, 39
	v_max3_f32 v32, v32, v58, v55
	v_cndmask_b32_e64 v35, v20, v200, s[74:75]
	v_cndmask_b32_e64 v56, v36, v200, s[0:1]
	v_readlane_b32 s0, v255, 40
	v_readlane_b32 s1, v255, 41
	v_cndmask_b32_e64 v36, v19, v200, s[72:73]
	v_cndmask_b32_e64 v33, v22, v200, s[78:79]
	v_cndmask_b32_e64 v53, v37, v200, s[0:1]
	v_readlane_b32 s0, v255, 42
	v_readlane_b32 s1, v255, 43
	v_max3_f32 v32, v32, v56, v53
	v_cndmask_b32_e64 v37, v18, v200, s[70:71]
	v_cndmask_b32_e64 v54, v38, v200, s[0:1]
	v_cmp_gt_i32_e64 s[0:1], v100, v96
	s_or_b64 s[0:1], vcc, s[0:1]
	s_or_b64 vcc, s[0:1], s[42:43]
	v_cndmask_b32_e32 v0, v0, v200, vcc
	v_cmp_le_i32_e32 vcc, v119, v96
	v_cmp_gt_i32_e64 s[0:1], v119, v94
	s_or_b64 s[0:1], vcc, s[0:1]
	s_or_b64 vcc, s[0:1], s[4:5]
	v_cndmask_b32_e32 v1, v1, v200, vcc
	v_cmp_le_i32_e32 vcc, v120, v96
	v_cmp_gt_i32_e64 s[0:1], v120, v94
	s_or_b64 s[0:1], vcc, s[0:1]
	s_or_b64 vcc, s[0:1], s[48:49]
	v_cndmask_b32_e32 v2, v2, v200, vcc
	v_cmp_le_i32_e32 vcc, v121, v96
	v_cmp_gt_i32_e64 s[0:1], v121, v94
	s_or_b64 s[0:1], vcc, s[0:1]
	s_or_b64 vcc, s[0:1], s[8:9]
	v_cndmask_b32_e32 v3, v3, v200, vcc
	v_cmp_le_i32_e32 vcc, v122, v96
	v_cmp_gt_i32_e64 s[0:1], v122, v94
	s_or_b64 s[0:1], vcc, s[0:1]
	s_or_b64 vcc, s[0:1], s[10:11]
	v_cndmask_b32_e32 v4, v4, v200, vcc
	v_cmp_le_i32_e32 vcc, v123, v96
	v_cmp_gt_i32_e64 s[0:1], v123, v94
	s_or_b64 s[0:1], vcc, s[0:1]
	s_or_b64 vcc, s[0:1], s[12:13]
	v_cndmask_b32_e32 v5, v5, v200, vcc
	v_cmp_le_i32_e32 vcc, v124, v96
	v_cmp_gt_i32_e64 s[0:1], v124, v94
	s_or_b64 s[0:1], vcc, s[0:1]
	s_or_b64 vcc, s[0:1], s[14:15]
	v_cndmask_b32_e32 v6, v6, v200, vcc
	v_cmp_le_i32_e32 vcc, v125, v96
	v_cmp_gt_i32_e64 s[0:1], v125, v94
	s_or_b64 s[0:1], vcc, s[0:1]
	s_or_b64 vcc, s[0:1], s[16:17]
	v_cndmask_b32_e32 v7, v7, v200, vcc
	v_cmp_le_i32_e32 vcc, v126, v96
	v_cmp_gt_i32_e64 s[0:1], v126, v94
	s_or_b64 s[0:1], vcc, s[0:1]
	s_or_b64 vcc, s[0:1], s[18:19]
	v_cndmask_b32_e32 v8, v8, v200, vcc
	v_cmp_le_i32_e32 vcc, v127, v96
	v_cmp_gt_i32_e64 s[0:1], v127, v94
	s_or_b64 s[0:1], vcc, s[0:1]
	s_or_b64 vcc, s[0:1], s[20:21]
	v_max3_f32 v32, v32, v54, v52
	v_cndmask_b32_e32 v9, v9, v200, vcc
	v_cmp_le_i32_e32 vcc, v128, v96
	v_cmp_gt_i32_e64 s[0:1], v128, v94
	v_max3_f32 v32, v32, v51, v50
	s_or_b64 s[0:1], vcc, s[0:1]
	v_max3_f32 v32, v32, v49, v48
	s_or_b64 vcc, s[0:1], s[22:23]
	v_max3_f32 v32, v32, v43, v42
	v_cndmask_b32_e32 v10, v10, v200, vcc
	v_cmp_le_i32_e32 vcc, v129, v96
	v_cmp_gt_i32_e64 s[0:1], v129, v94
	v_max3_f32 v32, v32, v41, v40
	v_cndmask_b32_e64 v38, v17, v200, s[68:69]
	s_or_b64 s[0:1], vcc, s[0:1]
	v_max3_f32 v16, v32, v39, v38
	s_or_b64 vcc, s[0:1], s[24:25]
	v_max3_f32 v16, v16, v37, v36
	v_cndmask_b32_e32 v11, v11, v200, vcc
	v_cmp_le_i32_e32 vcc, v130, v96
	v_cmp_gt_i32_e64 s[0:1], v130, v94
	v_max3_f32 v16, v16, v35, v34
	v_cndmask_b32_e64 v32, v23, v200, s[80:81]
	s_or_b64 s[0:1], vcc, s[0:1]
	v_max3_f32 v16, v16, v33, v32
	v_cndmask_b32_e64 v23, v24, v200, s[82:83]
	v_cndmask_b32_e64 v22, v25, v200, s[84:85]
	s_or_b64 vcc, s[0:1], s[26:27]
	v_max3_f32 v16, v16, v23, v22
	v_cndmask_b32_e64 v21, v26, v200, s[86:87]
	v_cndmask_b32_e64 v20, v27, v200, s[88:89]
	v_cndmask_b32_e32 v12, v12, v200, vcc
	v_cmp_le_i32_e32 vcc, v131, v96
	v_cmp_gt_i32_e64 s[0:1], v131, v94
	v_max3_f32 v16, v16, v21, v20
	v_cndmask_b32_e64 v19, v28, v200, s[90:91]
	v_cndmask_b32_e64 v18, v29, v200, s[92:93]
	s_or_b64 s[0:1], vcc, s[0:1]
	v_max3_f32 v24, v16, v19, v18
	v_cndmask_b32_e64 v17, v30, v200, s[94:95]
	v_cndmask_b32_e64 v16, v31, v200, s[96:97]
	s_or_b64 vcc, s[0:1], s[28:29]
	v_max3_f32 v24, v24, v17, v16
	v_cndmask_b32_e32 v13, v13, v200, vcc
	v_cmp_le_i32_e32 vcc, v132, v96
	v_cmp_gt_i32_e64 s[0:1], v132, v94
	v_max3_f32 v24, v24, v0, v1
	s_or_b64 s[0:1], vcc, s[0:1]
	v_max3_f32 v24, v24, v2, v3
	s_or_b64 vcc, s[0:1], s[30:31]
	v_max3_f32 v24, v24, v4, v5
	v_cndmask_b32_e32 v14, v14, v200, vcc
	v_cmp_le_i32_e32 vcc, v133, v96
	v_cmp_gt_i32_e64 s[0:1], v133, v94
	v_max3_f32 v24, v24, v6, v7
	s_or_b64 s[0:1], vcc, s[0:1]
	v_max3_f32 v24, v24, v8, v9
	s_or_b64 vcc, s[0:1], s[34:35]
	v_max3_f32 v24, v24, v10, v11
	v_cndmask_b32_e32 v15, v15, v200, vcc
	v_max3_f32 v24, v24, v12, v13
	v_max3_f32 v24, v24, v14, v15
	v_mov_b32_e32 v26, v24
	v_mov_b32_e32 v226, v24
	s_nop 1
	v_permlane32_swap_b32_e32 v26, v226
	s_lshr_b32 s1, s39, 2
	s_mulk_i32 s1, 0x4080
	s_add_i32 s2, s1, 0x20400
	s_add_i32 s0, s44, s33
	s_waitcnt lgkmcnt(0)
	v_max_f32_e32 v24, v26, v226
	v_sub_f32_e32 v26, v64, v24
	v_mul_f32_e32 v26, 0x3fb8aa3b, v26
	v_sub_f32_e32 v28, v65, v24
	v_exp_f32_e32 v26, v26
	v_mul_f32_e32 v28, 0x3fb8aa3b, v28
	v_sub_f32_e32 v29, v66, v24
	v_exp_f32_e32 v28, v28
	v_mul_f32_e32 v29, 0x3fb8aa3b, v29
	v_sub_f32_e32 v30, v67, v24
	v_exp_f32_e32 v29, v29
	v_mul_f32_e32 v30, 0x3fb8aa3b, v30
	v_sub_f32_e32 v31, v68, v24
	v_exp_f32_e32 v30, v30
	v_mul_f32_e32 v31, 0x3fb8aa3b, v31
	v_sub_f32_e32 v44, v69, v24
	v_add_f32_e32 v27, 0, v26
	v_exp_f32_e32 v31, v31
	v_mul_f32_e32 v44, 0x3fb8aa3b, v44
	v_sub_f32_e32 v45, v70, v24
	v_add_f32_e32 v27, v28, v27
	v_exp_f32_e32 v44, v44
	v_mul_f32_e32 v45, 0x3fb8aa3b, v45
	v_sub_f32_e32 v46, v71, v24
	v_add_f32_e32 v27, v29, v27
	v_exp_f32_e32 v45, v45
	v_mul_f32_e32 v46, 0x3fb8aa3b, v46
	v_sub_f32_e32 v47, v72, v24
	v_add_f32_e32 v27, v30, v27
	v_exp_f32_e32 v46, v46
	v_mul_f32_e32 v47, 0x3fb8aa3b, v47
	v_sub_f32_e32 v63, v73, v24
	v_add_f32_e32 v27, v31, v27
	v_exp_f32_e32 v47, v47
	v_mul_f32_e32 v63, 0x3fb8aa3b, v63
	v_sub_f32_e32 v64, v74, v24
	v_add_f32_e32 v27, v44, v27
	v_exp_f32_e32 v63, v63
	v_mul_f32_e32 v64, 0x3fb8aa3b, v64
	v_sub_f32_e32 v65, v75, v24
	v_add_f32_e32 v27, v45, v27
	v_exp_f32_e32 v64, v64
	v_mul_f32_e32 v65, 0x3fb8aa3b, v65
	v_sub_f32_e32 v66, v76, v24
	v_add_f32_e32 v27, v46, v27
	v_exp_f32_e32 v65, v65
	v_mul_f32_e32 v66, 0x3fb8aa3b, v66
	v_sub_f32_e32 v67, v77, v24
	v_add_f32_e32 v27, v47, v27
	v_exp_f32_e32 v66, v66
	v_mul_f32_e32 v67, 0x3fb8aa3b, v67
	v_sub_f32_e32 v68, v85, v24
	v_add_f32_e32 v27, v63, v27
	v_exp_f32_e32 v67, v67
	v_mul_f32_e32 v68, 0x3fb8aa3b, v68
	v_sub_f32_e32 v69, v92, v24
	v_add_f32_e32 v27, v64, v27
	v_exp_f32_e32 v68, v68
	v_mul_f32_e32 v69, 0x3fb8aa3b, v69
	v_sub_f32_e32 v70, v93, v24
	v_add_f32_e32 v27, v65, v27
	v_exp_f32_e32 v69, v69
	v_mul_f32_e32 v70, 0x3fb8aa3b, v70
	v_sub_f32_e32 v71, v90, v24
	v_add_f32_e32 v27, v66, v27
	v_exp_f32_e32 v70, v70
	v_mul_f32_e32 v71, 0x3fb8aa3b, v71
	v_sub_f32_e32 v72, v91, v24
	v_add_f32_e32 v27, v67, v27
	v_exp_f32_e32 v71, v71
	v_mul_f32_e32 v72, 0x3fb8aa3b, v72
	v_sub_f32_e32 v73, v88, v24
	v_add_f32_e32 v27, v68, v27
	v_exp_f32_e32 v72, v72
	v_mul_f32_e32 v73, 0x3fb8aa3b, v73
	v_sub_f32_e32 v74, v89, v24
	v_add_f32_e32 v27, v69, v27
	v_exp_f32_e32 v73, v73
	v_mul_f32_e32 v74, 0x3fb8aa3b, v74
	v_sub_f32_e32 v75, v86, v24
	v_add_f32_e32 v27, v70, v27
	v_exp_f32_e32 v74, v74
	v_mul_f32_e32 v75, 0x3fb8aa3b, v75
	v_sub_f32_e32 v76, v87, v24
	v_add_f32_e32 v27, v71, v27
	v_exp_f32_e32 v75, v75
	v_mul_f32_e32 v76, 0x3fb8aa3b, v76
	v_sub_f32_e32 v77, v83, v24
	v_add_f32_e32 v27, v72, v27
	v_exp_f32_e32 v76, v76
	v_mul_f32_e32 v77, 0x3fb8aa3b, v77
	v_sub_f32_e32 v83, v84, v24
	v_add_f32_e32 v27, v73, v27
	v_exp_f32_e32 v77, v77
	v_mul_f32_e32 v83, 0x3fb8aa3b, v83
	v_sub_f32_e32 v81, v81, v24
	v_add_f32_e32 v27, v74, v27
	v_exp_f32_e32 v83, v83
	v_mul_f32_e32 v81, 0x3fb8aa3b, v81
	v_sub_f32_e32 v82, v82, v24
	v_add_f32_e32 v27, v75, v27
	v_exp_f32_e32 v81, v81
	v_mul_f32_e32 v82, 0x3fb8aa3b, v82
	v_sub_f32_e32 v78, v78, v24
	v_add_f32_e32 v27, v76, v27
	v_exp_f32_e32 v82, v82
	v_mul_f32_e32 v78, 0x3fb8aa3b, v78
	v_sub_f32_e32 v79, v79, v24
	v_add_f32_e32 v27, v77, v27
	v_exp_f32_e32 v78, v78
	v_mul_f32_e32 v79, 0x3fb8aa3b, v79
	v_sub_f32_e32 v61, v61, v24
	v_add_f32_e32 v27, v83, v27
	v_exp_f32_e32 v79, v79
	v_mul_f32_e32 v61, 0x3fb8aa3b, v61
	v_sub_f32_e32 v62, v62, v24
	v_add_f32_e32 v27, v81, v27
	v_exp_f32_e32 v61, v61
	v_mul_f32_e32 v62, 0x3fb8aa3b, v62
	v_sub_f32_e32 v59, v59, v24
	v_add_f32_e32 v27, v82, v27
	v_exp_f32_e32 v62, v62
	v_mul_f32_e32 v59, 0x3fb8aa3b, v59
	v_sub_f32_e32 v60, v60, v24
	v_add_f32_e32 v27, v78, v27
	v_exp_f32_e32 v59, v59
	v_mul_f32_e32 v60, 0x3fb8aa3b, v60
	v_sub_f32_e32 v57, v57, v24
	v_add_f32_e32 v27, v79, v27
	v_exp_f32_e32 v60, v60
	v_mul_f32_e32 v57, 0x3fb8aa3b, v57
	v_sub_f32_e32 v58, v58, v24
	v_add_f32_e32 v27, v61, v27
	v_exp_f32_e32 v57, v57
	v_mul_f32_e32 v58, 0x3fb8aa3b, v58
	v_sub_f32_e32 v55, v55, v24
	v_add_f32_e32 v27, v62, v27
	v_exp_f32_e32 v58, v58
	v_mul_f32_e32 v55, 0x3fb8aa3b, v55
	v_sub_f32_e32 v56, v56, v24
	v_add_f32_e32 v27, v59, v27
	v_exp_f32_e32 v55, v55
	v_mul_f32_e32 v56, 0x3fb8aa3b, v56
	v_sub_f32_e32 v53, v53, v24
	v_add_f32_e32 v27, v60, v27
	v_exp_f32_e32 v56, v56
	v_mul_f32_e32 v53, 0x3fb8aa3b, v53
	v_sub_f32_e32 v54, v54, v24
	v_add_f32_e32 v27, v57, v27
	v_exp_f32_e32 v53, v53
	v_mul_f32_e32 v54, 0x3fb8aa3b, v54
	v_sub_f32_e32 v52, v52, v24
	v_add_f32_e32 v27, v58, v27
	v_exp_f32_e32 v54, v54
	v_mul_f32_e32 v52, 0x3fb8aa3b, v52
	v_sub_f32_e32 v51, v51, v24
	v_add_f32_e32 v27, v55, v27
	v_exp_f32_e32 v52, v52
	v_mul_f32_e32 v51, 0x3fb8aa3b, v51
	v_sub_f32_e32 v50, v50, v24
	v_add_f32_e32 v27, v56, v27
	v_exp_f32_e32 v51, v51
	v_mul_f32_e32 v50, 0x3fb8aa3b, v50
	v_sub_f32_e32 v49, v49, v24
	v_add_f32_e32 v27, v53, v27
	v_exp_f32_e32 v50, v50
	v_mul_f32_e32 v49, 0x3fb8aa3b, v49
	v_sub_f32_e32 v48, v48, v24
	v_add_f32_e32 v27, v54, v27
	v_exp_f32_e32 v49, v49
	v_mul_f32_e32 v48, 0x3fb8aa3b, v48
	v_sub_f32_e32 v43, v43, v24
	v_add_f32_e32 v27, v52, v27
	v_exp_f32_e32 v48, v48
	v_mul_f32_e32 v43, 0x3fb8aa3b, v43
	v_sub_f32_e32 v42, v42, v24
	v_add_f32_e32 v27, v51, v27
	v_exp_f32_e32 v84, v43
	v_mul_f32_e32 v42, 0x3fb8aa3b, v42
	v_sub_f32_e32 v41, v41, v24
	v_add_f32_e32 v27, v50, v27
	v_exp_f32_e32 v85, v42
	v_mul_f32_e32 v41, 0x3fb8aa3b, v41
	v_sub_f32_e32 v40, v40, v24
	v_add_f32_e32 v27, v49, v27
	v_exp_f32_e32 v86, v41
	v_mul_f32_e32 v40, 0x3fb8aa3b, v40
	v_sub_f32_e32 v39, v39, v24
	v_add_f32_e32 v27, v48, v27
	v_exp_f32_e32 v87, v40
	v_mul_f32_e32 v39, 0x3fb8aa3b, v39
	v_sub_f32_e32 v38, v38, v24
	v_add_f32_e32 v27, v84, v27
	v_exp_f32_e32 v88, v39
	v_mul_f32_e32 v38, 0x3fb8aa3b, v38
	v_sub_f32_e32 v37, v37, v24
	v_add_f32_e32 v27, v85, v27
	v_exp_f32_e32 v89, v38
	v_mul_f32_e32 v37, 0x3fb8aa3b, v37
	v_sub_f32_e32 v36, v36, v24
	v_sub_f32_e32 v1, v1, v24
	v_add_f32_e32 v27, v86, v27
	v_exp_f32_e32 v90, v37
	v_mul_f32_e32 v36, 0x3fb8aa3b, v36
	v_sub_f32_e32 v35, v35, v24
	v_mul_f32_e32 v1, 0x3fb8aa3b, v1
	v_add_f32_e32 v27, v87, v27
	v_exp_f32_e32 v91, v36
	v_mul_f32_e32 v35, 0x3fb8aa3b, v35
	v_sub_f32_e32 v34, v34, v24
	v_exp_f32_e32 v142, v1
	v_sub_f32_e32 v1, v2, v24
	v_add_f32_e32 v27, v88, v27
	v_exp_f32_e32 v35, v35
	v_mul_f32_e32 v34, 0x3fb8aa3b, v34
	v_sub_f32_e32 v33, v33, v24
	v_mul_f32_e32 v1, 0x3fb8aa3b, v1
	v_add_f32_e32 v27, v89, v27
	v_exp_f32_e32 v92, v34
	v_mul_f32_e32 v33, 0x3fb8aa3b, v33
	v_sub_f32_e32 v32, v32, v24
	v_exp_f32_e32 v143, v1
	v_sub_f32_e32 v1, v3, v24
	v_add_f32_e32 v27, v90, v27
	v_exp_f32_e32 v33, v33
	v_mul_f32_e32 v32, 0x3fb8aa3b, v32
	v_sub_f32_e32 v23, v23, v24
	v_mul_f32_e32 v1, 0x3fb8aa3b, v1
	v_add_f32_e32 v27, v91, v27
	v_exp_f32_e32 v32, v32
	v_mul_f32_e32 v23, 0x3fb8aa3b, v23
	v_sub_f32_e32 v22, v22, v24
	v_exp_f32_e32 v144, v1
	v_sub_f32_e32 v1, v4, v24
	v_add_f32_e32 v27, v35, v27
	v_exp_f32_e32 v93, v23
	v_mul_f32_e32 v22, 0x3fb8aa3b, v22
	v_sub_f32_e32 v21, v21, v24
	v_mul_f32_e32 v1, 0x3fb8aa3b, v1
	v_add_f32_e32 v27, v92, v27
	v_exp_f32_e32 v94, v22
	v_mul_f32_e32 v21, 0x3fb8aa3b, v21
	v_sub_f32_e32 v20, v20, v24
	v_exp_f32_e32 v145, v1
	v_sub_f32_e32 v1, v5, v24
	v_add_f32_e32 v27, v33, v27
	v_exp_f32_e32 v95, v21
	v_mul_f32_e32 v20, 0x3fb8aa3b, v20
	v_sub_f32_e32 v19, v19, v24
	v_mul_f32_e32 v1, 0x3fb8aa3b, v1
	v_add_f32_e32 v27, v32, v27
	v_exp_f32_e32 v96, v20
	v_mul_f32_e32 v19, 0x3fb8aa3b, v19
	v_sub_f32_e32 v18, v18, v24
	v_exp_f32_e32 v146, v1
	v_sub_f32_e32 v1, v6, v24
	v_add_f32_e32 v23, v93, v27
	v_exp_f32_e32 v137, v19
	v_mul_f32_e32 v18, 0x3fb8aa3b, v18
	v_sub_f32_e32 v17, v17, v24
	v_mul_f32_e32 v1, 0x3fb8aa3b, v1
	v_add_f32_e32 v22, v94, v23
	v_exp_f32_e32 v138, v18
	v_mul_f32_e32 v17, 0x3fb8aa3b, v17
	v_sub_f32_e32 v16, v16, v24
	v_exp_f32_e32 v147, v1
	v_sub_f32_e32 v1, v7, v24
	v_add_f32_e32 v21, v95, v22
	v_exp_f32_e32 v139, v17
	v_mul_f32_e32 v16, 0x3fb8aa3b, v16
	v_sub_f32_e32 v0, v0, v24
	v_mul_f32_e32 v1, 0x3fb8aa3b, v1
	v_add_f32_e32 v20, v96, v21
	v_exp_f32_e32 v140, v16
	v_mul_f32_e32 v0, 0x3fb8aa3b, v0
	v_exp_f32_e32 v148, v1
	v_sub_f32_e32 v1, v8, v24
	v_add_f32_e32 v19, v137, v20
	v_exp_f32_e32 v141, v0
	v_mul_f32_e32 v1, 0x3fb8aa3b, v1
	v_add_f32_e32 v18, v138, v19
	v_exp_f32_e32 v149, v1
	v_sub_f32_e32 v1, v9, v24
	v_add_f32_e32 v17, v139, v18
	v_mul_f32_e32 v1, 0x3fb8aa3b, v1
	v_add_f32_e32 v16, v140, v17
	v_exp_f32_e32 v150, v1
	v_sub_f32_e32 v1, v10, v24
	v_add_f32_e32 v0, v141, v16
	v_mul_f32_e32 v1, 0x3fb8aa3b, v1
	v_add_f32_e32 v0, v142, v0
	v_exp_f32_e32 v151, v1
	v_sub_f32_e32 v1, v11, v24
	v_add_f32_e32 v0, v143, v0
	v_mul_f32_e32 v1, 0x3fb8aa3b, v1
	v_add_f32_e32 v0, v144, v0
	v_exp_f32_e32 v152, v1
	v_sub_f32_e32 v1, v12, v24
	v_add_f32_e32 v0, v145, v0
	v_mul_f32_e32 v1, 0x3fb8aa3b, v1
	v_add_f32_e32 v0, v146, v0
	v_exp_f32_e32 v153, v1
	v_sub_f32_e32 v1, v13, v24
	v_add_f32_e32 v0, v147, v0
	v_mul_f32_e32 v1, 0x3fb8aa3b, v1
	v_add_f32_e32 v0, v148, v0
	v_exp_f32_e32 v154, v1
	v_sub_f32_e32 v1, v14, v24
	v_add_f32_e32 v0, v149, v0
	v_mul_f32_e32 v1, 0x3fb8aa3b, v1
	v_add_f32_e32 v0, v150, v0
	v_exp_f32_e32 v155, v1
	v_sub_f32_e32 v1, v15, v24
	v_add_f32_e32 v0, v151, v0
	v_mul_f32_e32 v1, 0x3fb8aa3b, v1
	v_add_f32_e32 v0, v152, v0
	v_exp_f32_e32 v156, v1
	v_add_f32_e32 v0, v153, v0
	v_add_f32_e32 v0, v154, v0
	v_add_f32_e32 v0, v155, v0
	v_add_f32_e32 v0, v156, v0
	v_mov_b32_e32 v1, v0
	v_mov_b32_e32 v227, v0
	s_nop 1
	v_permlane32_swap_b32_e32 v1, v227
	v_cvt_pk_bf16_f32 v2, v31, v44
	v_add_u32_e32 v44, 0x9000, v136
	ds_read2_b64 v[4:7], v44 offset1:2
	ds_read2_b64 v[36:39], v44 offset0:4 offset1:6
	v_cvt_pk_bf16_f32 v3, v45, v46
	s_waitcnt lgkmcnt(2)
	v_add_f32_e32 v0, v1, v227
	v_sub_f32_e32 v1, v80, v24
	v_mul_f32_e32 v1, 0x3fb8aa3b, v1
	v_exp_f32_e32 v1, v1
	v_add_u32_e32 v45, 0xd000, v136
	v_cvt_pk_bf16_f32 v40, v47, v63
	v_cvt_pk_bf16_f32 v41, v64, v65
	v_add_f32_e32 v34, v1, v0
	v_cvt_pk_bf16_f32 v0, v26, v28
	v_cvt_pk_bf16_f32 v1, v29, v30
	v_cvt_pk_bf16_f32 v42, v66, v67
	v_cvt_pk_bf16_f32 v43, v68, v69
	s_waitcnt lgkmcnt(1)
	v_mfma_f32_32x32x16_bf16 v[16:31], v[4:7], v[0:3], 0
	ds_read2_b64 v[4:7], v45 offset0:96 offset1:98
	s_and_b32 s0, s0, 0xc0
	s_mov_b64 vcc, s[46:47]
	v_readlane_b32 s1, v254, 36
	s_add_i32 s33, s33, 64
	v_mov_b32_e32 v203, 0
	v_lshl_add_u64 v[192:193], s[2:3], 0, v[98:99]
	v_lshlrev_b64 v[192:193], 9, v[192:193]
	v_lshl_add_u64 v[192:193], vcc, 0, v[192:193]
	s_lshl_b32 s2, s0, 1
	v_lshl_add_u64 v[192:193], v[192:193], 0, s[2:3]
	s_and_b32 s0, s38, 4
	s_or_b32 s0, s0, s1
	s_lshr_b32 s0, s0, 2
	v_lshlrev_b32_e32 v202, 1, v100
	v_lshl_add_u64 v[192:193], v[192:193], 0, v[202:203]
	s_mul_i32 s2, s0, 0x4080
	v_lshl_add_u64 v[194:195], s[2:3], 0, v[98:99]
	s_and_b32 s0, s33, 0xc0
	v_or_b32_e32 v196, s0, v134
	v_lshlrev_b64 v[194:195], 9, v[194:195]
	v_lshl_add_u64 v[194:195], vcc, 0, v[194:195]
	v_lshlrev_b32_e32 v202, 1, v196
	v_lshl_add_u64 v[194:195], v[194:195], 0, v[202:203]
	v_lshl_add_u64 v[224:225], v[192:193], 0, v[206:207]
	global_load_dwordx4 v[160:163], v[224:225], off
	global_load_dwordx4 v[164:167], v[224:225], off offset:32
	global_load_dwordx4 v[168:171], v[224:225], off offset:64
	global_load_dwordx4 v[172:175], v[224:225], off offset:96
	global_load_dwordx4 v[176:179], v[194:195], off
	global_load_dwordx4 v[180:183], v[194:195], off offset:32
	global_load_dwordx4 v[184:187], v[194:195], off offset:64
	global_load_dwordx4 v[188:191], v[194:195], off offset:96
	v_rcp_f32_e32 v34, v34
	s_waitcnt lgkmcnt(1)
	v_mfma_f32_32x32x16_bf16 v[16:31], v[36:39], v[40:43], v[16:31]
	ds_read2_b64 v[36:39], v45 offset0:100 offset1:102
	s_waitcnt lgkmcnt(1)
	v_mfma_f32_32x32x16_bf16 v[0:15], v[4:7], v[0:3], 0
	s_waitcnt lgkmcnt(0)
	v_mfma_f32_32x32x16_bf16 v[0:15], v[36:39], v[40:43], v[0:15]
	ds_read2_b64 v[40:43], v44 offset0:8 offset1:10
	v_cvt_pk_bf16_f32 v36, v70, v71
	v_cvt_pk_bf16_f32 v37, v72, v73
	v_cvt_pk_bf16_f32 v38, v74, v75
	v_cvt_pk_bf16_f32 v39, v76, v77
	s_waitcnt lgkmcnt(0)
	s_nop 0
	v_mfma_f32_32x32x16_bf16 v[16:31], v[40:43], v[36:39], v[16:31]
	ds_read2_b64 v[40:43], v45 offset0:104 offset1:106
	s_waitcnt lgkmcnt(0)
	v_mfma_f32_32x32x16_bf16 v[0:15], v[40:43], v[36:39], v[0:15]
	ds_read2_b64 v[40:43], v44 offset0:12 offset1:14
	v_cvt_pk_bf16_f32 v36, v83, v81
	v_cvt_pk_bf16_f32 v37, v82, v78
	v_cvt_pk_bf16_f32 v38, v79, v61
	v_cvt_pk_bf16_f32 v39, v62, v59
	s_waitcnt lgkmcnt(0)
	s_nop 0
	v_mfma_f32_32x32x16_bf16 v[16:31], v[40:43], v[36:39], v[16:31]
	ds_read2_b64 v[40:43], v45 offset0:108 offset1:110
	s_waitcnt lgkmcnt(0)
	v_mfma_f32_32x32x16_bf16 v[0:15], v[40:43], v[36:39], v[0:15]
	ds_read2_b64 v[40:43], v44 offset0:16 offset1:18
	v_cvt_pk_bf16_f32 v36, v60, v57
	v_cvt_pk_bf16_f32 v37, v58, v55
	v_cvt_pk_bf16_f32 v38, v56, v53
	v_cvt_pk_bf16_f32 v39, v54, v52
	s_waitcnt lgkmcnt(0)
	s_nop 0
	v_mfma_f32_32x32x16_bf16 v[16:31], v[40:43], v[36:39], v[16:31]
	ds_read2_b64 v[40:43], v45 offset0:112 offset1:114
	s_waitcnt lgkmcnt(0)
	v_mfma_f32_32x32x16_bf16 v[0:15], v[40:43], v[36:39], v[0:15]
	ds_read2_b64 v[40:43], v44 offset0:20 offset1:22
	v_cvt_pk_bf16_f32 v36, v51, v50
	v_cvt_pk_bf16_f32 v37, v49, v48
	v_cvt_pk_bf16_f32 v38, v84, v85
	v_cvt_pk_bf16_f32 v39, v86, v87
	s_waitcnt lgkmcnt(0)
	s_nop 0
	v_mfma_f32_32x32x16_bf16 v[16:31], v[40:43], v[36:39], v[16:31]
	ds_read2_b64 v[40:43], v45 offset0:116 offset1:118
	s_waitcnt lgkmcnt(0)
	v_mfma_f32_32x32x16_bf16 v[0:15], v[40:43], v[36:39], v[0:15]
	ds_read2_b64 v[40:43], v44 offset0:24 offset1:26
	v_cvt_pk_bf16_f32 v36, v88, v89
	v_cvt_pk_bf16_f32 v37, v90, v91
	v_cvt_pk_bf16_f32 v38, v35, v92
	v_cvt_pk_bf16_f32 v39, v33, v32
	s_waitcnt lgkmcnt(0)
	s_nop 0
	v_mfma_f32_32x32x16_bf16 v[16:31], v[40:43], v[36:39], v[16:31]
	ds_read2_b64 v[40:43], v45 offset0:120 offset1:122
	s_waitcnt lgkmcnt(0)
	v_mfma_f32_32x32x16_bf16 v[0:15], v[40:43], v[36:39], v[0:15]
	ds_read2_b64 v[40:43], v44 offset0:28 offset1:30
	v_cvt_pk_bf16_f32 v36, v93, v94
	v_cvt_pk_bf16_f32 v37, v95, v96
	v_cvt_pk_bf16_f32 v38, v137, v138
	v_cvt_pk_bf16_f32 v39, v139, v140
	s_waitcnt lgkmcnt(0)
	s_nop 0
	v_mfma_f32_32x32x16_bf16 v[16:31], v[40:43], v[36:39], v[16:31]
	ds_read2_b64 v[40:43], v45 offset0:124 offset1:126
	s_waitcnt lgkmcnt(0)
	v_mfma_f32_32x32x16_bf16 v[0:15], v[40:43], v[36:39], v[0:15]
	ds_read2_b64 v[40:43], v44 offset0:32 offset1:34
	v_cvt_pk_bf16_f32 v36, v141, v142
	v_cvt_pk_bf16_f32 v37, v143, v144
	v_cvt_pk_bf16_f32 v38, v145, v146
	v_cvt_pk_bf16_f32 v39, v147, v148
	s_waitcnt lgkmcnt(0)
	s_nop 0
	v_mfma_f32_32x32x16_bf16 v[16:31], v[40:43], v[36:39], v[16:31]
	ds_read2_b64 v[40:43], v45 offset0:128 offset1:130
	s_add_u32 s36, s36, 4
	s_addc_u32 s37, s37, 0
	s_mov_b64 s[0:1], 0x80
	s_cmp_eq_u32 s38, 8
	s_waitcnt lgkmcnt(0)
	v_mfma_f32_32x32x16_bf16 v[0:15], v[40:43], v[36:39], v[0:15]
	ds_read2_b64 v[40:43], v44 offset0:36 offset1:38
	v_cvt_pk_bf16_f32 v36, v149, v150
	v_cvt_pk_bf16_f32 v37, v151, v152
	v_cvt_pk_bf16_f32 v38, v153, v154
	v_cvt_pk_bf16_f32 v39, v155, v156
	s_waitcnt lgkmcnt(0)
	s_nop 0
	v_mfma_f32_32x32x16_bf16 v[16:31], v[40:43], v[36:39], v[16:31]
	ds_read2_b64 v[40:43], v45 offset0:132 offset1:134
	s_waitcnt lgkmcnt(0)
	v_mfma_f32_32x32x16_bf16 v[0:15], v[40:43], v[36:39], v[0:15]
	s_nop 0
	s_nop 0
	s_nop 6
	v_pk_mul_f32 v[16:17], v[16:17], v[34:35] op_sel_hi:[1,0]
	v_pk_mul_f32 v[18:19], v[18:19], v[34:35] op_sel_hi:[1,0]
	s_nop 0
	v_pk_mul_f32 v[0:1], v[0:1], v[34:35] op_sel_hi:[1,0]
	v_pk_mul_f32 v[2:3], v[2:3], v[34:35] op_sel_hi:[1,0]
	v_lshl_add_u64 v[204:205], v[102:103], 0, v[206:207]
	s_waitcnt vmcnt(7)
	s_nop 1
	v_permlane32_swap_b32_e32 v160, v162
	v_permlane32_swap_b32_e32 v161, v163
	v_lshlrev_b32_e32 v50, 16, v160
	v_and_b32_e32 v51, 0xffff0000, v160
	v_lshlrev_b32_e32 v48, 16, v161
	v_and_b32_e32 v49, 0xffff0000, v161
	v_pk_mul_f32 v[16:17], v[16:17], v[50:51]
	v_pk_mul_f32 v[18:19], v[18:19], v[48:49]
	v_cvt_pk_bf16_f32 v208, v16, v17
	v_cvt_pk_bf16_f32 v209, v18, v19
	v_pk_mul_f32 v[16:17], v[20:21], v[34:35] op_sel_hi:[1,0]
	s_waitcnt vmcnt(7)
	v_lshlrev_b32_e32 v18, 16, v162
	v_and_b32_e32 v19, 0xffff0000, v162
	v_pk_mul_f32 v[16:17], v[16:17], v[18:19]
	v_pk_mul_f32 v[18:19], v[22:23], v[34:35] op_sel_hi:[1,0]
	v_lshlrev_b32_e32 v20, 16, v163
	v_and_b32_e32 v21, 0xffff0000, v163
	v_pk_mul_f32 v[18:19], v[18:19], v[20:21]
	v_cvt_pk_bf16_f32 v210, v16, v17
	v_cvt_pk_bf16_f32 v211, v18, v19
	s_nop 1
	v_permlane32_swap_b32_e32 v208, v210
	v_permlane32_swap_b32_e32 v209, v211
	global_store_dwordx4 v[204:205], v[208:211], off offset:-64
	v_pk_mul_f32 v[16:17], v[24:25], v[34:35] op_sel_hi:[1,0]
	s_waitcnt vmcnt(7)
	s_nop 1
	v_permlane32_swap_b32_e32 v164, v166
	v_permlane32_swap_b32_e32 v165, v167
	v_lshlrev_b32_e32 v18, 16, v164
	v_and_b32_e32 v19, 0xffff0000, v164
	v_pk_mul_f32 v[16:17], v[16:17], v[18:19]
	v_pk_mul_f32 v[18:19], v[26:27], v[34:35] op_sel_hi:[1,0]
	v_lshlrev_b32_e32 v20, 16, v165
	v_and_b32_e32 v21, 0xffff0000, v165
	v_pk_mul_f32 v[18:19], v[18:19], v[20:21]
	v_cvt_pk_bf16_f32 v212, v16, v17
	v_cvt_pk_bf16_f32 v213, v18, v19
	v_pk_mul_f32 v[16:17], v[28:29], v[34:35] op_sel_hi:[1,0]
	s_waitcnt vmcnt(7)
	v_lshlrev_b32_e32 v18, 16, v166
	v_and_b32_e32 v19, 0xffff0000, v166
	v_pk_mul_f32 v[16:17], v[16:17], v[18:19]
	v_pk_mul_f32 v[18:19], v[30:31], v[34:35] op_sel_hi:[1,0]
	v_lshlrev_b32_e32 v20, 16, v167
	v_and_b32_e32 v21, 0xffff0000, v167
	v_pk_mul_f32 v[18:19], v[18:19], v[20:21]
	v_cvt_pk_bf16_f32 v214, v16, v17
	v_cvt_pk_bf16_f32 v215, v18, v19
	s_nop 1
	v_permlane32_swap_b32_e32 v212, v214
	v_permlane32_swap_b32_e32 v213, v215
	global_store_dwordx4 v[204:205], v[212:215], off offset:-32
	s_waitcnt vmcnt(7)
	s_nop 1
	v_permlane32_swap_b32_e32 v168, v170
	v_permlane32_swap_b32_e32 v169, v171
	v_lshlrev_b32_e32 v16, 16, v168
	v_and_b32_e32 v17, 0xffff0000, v168
	v_pk_mul_f32 v[0:1], v[0:1], v[16:17]
	v_lshlrev_b32_e32 v16, 16, v169
	v_and_b32_e32 v17, 0xffff0000, v169
	v_pk_mul_f32 v[2:3], v[2:3], v[16:17]
	v_cvt_pk_bf16_f32 v216, v0, v1
	v_cvt_pk_bf16_f32 v217, v2, v3
	v_pk_mul_f32 v[0:1], v[4:5], v[34:35] op_sel_hi:[1,0]
	s_waitcnt vmcnt(7)
	v_lshlrev_b32_e32 v2, 16, v170
	v_and_b32_e32 v3, 0xffff0000, v170
	v_pk_mul_f32 v[0:1], v[0:1], v[2:3]
	v_pk_mul_f32 v[2:3], v[6:7], v[34:35] op_sel_hi:[1,0]
	v_lshlrev_b32_e32 v4, 16, v171
	v_and_b32_e32 v5, 0xffff0000, v171
	v_pk_mul_f32 v[2:3], v[2:3], v[4:5]
	v_cvt_pk_bf16_f32 v218, v0, v1
	v_cvt_pk_bf16_f32 v219, v2, v3
	s_nop 1
	v_permlane32_swap_b32_e32 v216, v218
	v_permlane32_swap_b32_e32 v217, v219
	global_store_dwordx4 v[204:205], v[216:219], off
	v_pk_mul_f32 v[0:1], v[8:9], v[34:35] op_sel_hi:[1,0]
	s_waitcnt vmcnt(7)
	s_nop 1
	v_permlane32_swap_b32_e32 v172, v174
	v_permlane32_swap_b32_e32 v173, v175
	v_lshlrev_b32_e32 v2, 16, v172
	v_and_b32_e32 v3, 0xffff0000, v172
	v_pk_mul_f32 v[0:1], v[0:1], v[2:3]
	v_pk_mul_f32 v[2:3], v[10:11], v[34:35] op_sel_hi:[1,0]
	v_lshlrev_b32_e32 v4, 16, v173
	v_and_b32_e32 v5, 0xffff0000, v173
	v_pk_mul_f32 v[2:3], v[2:3], v[4:5]
	v_cvt_pk_bf16_f32 v220, v0, v1
	v_cvt_pk_bf16_f32 v221, v2, v3
	v_pk_mul_f32 v[0:1], v[12:13], v[34:35] op_sel_hi:[1,0]
	s_waitcnt vmcnt(7)
	v_lshlrev_b32_e32 v2, 16, v174
	v_and_b32_e32 v3, 0xffff0000, v174
	v_pk_mul_f32 v[0:1], v[0:1], v[2:3]
	v_pk_mul_f32 v[2:3], v[14:15], v[34:35] op_sel_hi:[1,0]
	v_lshlrev_b32_e32 v4, 16, v175
	v_and_b32_e32 v5, 0xffff0000, v175
	v_pk_mul_f32 v[2:3], v[2:3], v[4:5]
	v_cvt_pk_bf16_f32 v222, v0, v1
	v_cvt_pk_bf16_f32 v223, v2, v3
	s_nop 1
	v_permlane32_swap_b32_e32 v220, v222
	v_permlane32_swap_b32_e32 v221, v223
	global_store_dwordx4 v[204:205], v[220:223], off offset:32
	v_lshl_add_u64 v[102:103], v[102:103], 0, s[0:1]
	s_waitcnt vmcnt(4)
	v_mov_b32_e32 v80, v176
	v_mov_b32_e32 v81, v177
	v_mov_b32_e32 v82, v178
	v_mov_b32_e32 v83, v179
	v_mov_b32_e32 v84, v180
	v_mov_b32_e32 v85, v181
	v_mov_b32_e32 v86, v182
	v_mov_b32_e32 v87, v183
	v_mov_b32_e32 v88, v184
	v_mov_b32_e32 v89, v185
	v_mov_b32_e32 v90, v186
	v_mov_b32_e32 v91, v187
	v_mov_b32_e32 v92, v188
	v_mov_b32_e32 v93, v189
	v_mov_b32_e32 v94, v190
	v_mov_b32_e32 v95, v191
	s_cbranch_scc0 .LBB0_2056
	v_readlane_b32 s91, v254, 17
	v_readlane_b32 s24, v254, 52
	s_mov_b32 s37, s3
	s_movk_i32 s25, 0x90
	s_branch .LBB0_1999
